# new GEMM mainloop (LDS-DMA + fragment ring) also in phase G and phase H gate GEMM
# speedup vs baseline: 1.0687x; 1.0124x over previous
.Lgm_nodma1_B:
	ds_read_b128 v[64:67], v210 offset:0
	ds_read_b128 v[68:71], v210 offset:4096
	ds_read_b128 v[72:75], v214 offset:32768
	ds_read_b128 v[76:79], v214 offset:36864
	v_mfma_f32_32x32x16_bf16 v[48:63], v[80:83], v[88:91], v[48:63]
	v_mfma_f32_32x32x16_bf16 v[32:47], v[80:83], v[92:95], v[32:47]
	v_mfma_f32_32x32x16_bf16 v[16:31], v[84:87], v[88:91], v[16:31]
	v_mfma_f32_32x32x16_bf16 v[0:15], v[84:87], v[92:95], v[0:15]
	ds_read_b128 v[80:83], v211 offset:0
	ds_read_b128 v[84:87], v211 offset:4096
	ds_read_b128 v[88:91], v215 offset:32768
	ds_read_b128 v[92:95], v215 offset:36864
	v_mfma_f32_32x32x16_bf16 v[48:63], v[96:99], v[104:107], v[48:63]
	v_mfma_f32_32x32x16_bf16 v[32:47], v[96:99], v[108:111], v[32:47]
	v_mfma_f32_32x32x16_bf16 v[16:31], v[100:103], v[104:107], v[16:31]
	v_mfma_f32_32x32x16_bf16 v[0:15], v[100:103], v[108:111], v[0:15]
	ds_read_b128 v[96:99], v212 offset:0
	ds_read_b128 v[100:103], v212 offset:4096
	ds_read_b128 v[104:107], v216 offset:32768
	ds_read_b128 v[108:111], v216 offset:36864
	v_mfma_f32_32x32x16_bf16 v[48:63], v[112:115], v[120:123], v[48:63]
	v_mfma_f32_32x32x16_bf16 v[32:47], v[112:115], v[124:127], v[32:47]
	v_mfma_f32_32x32x16_bf16 v[16:31], v[116:119], v[120:123], v[16:31]
	v_mfma_f32_32x32x16_bf16 v[0:15], v[116:119], v[124:127], v[0:15]
	s_add_u32 s64, s64, 2
	s_cmp_lt_u32 s64, 32
	s_cbranch_scc1 .Lgm_loop_B
	s_waitcnt lgkmcnt(0)
	s_barrier
	s_nop 7

.LBB0_1012:
	s_lshl_b32 s6, s29, 7
	s_and_b32 s30, s6, 0x1f80
	s_lshl_b32 s6, s30, 12
	s_ashr_i32 s12, s29, 6
	s_lshl_b32 s14, s12, 7
	s_ashr_i32 s15, s14, 31
	s_lshl_b32 s26, s14, 12
	s_add_u32 s16, s88, 0x3f80000
	s_addc_u32 s17, s89, 0
	s_add_u32 s16, s16, s6
	s_addc_u32 s17, s17, 0
	s_add_u32 s20, s88, 0x2e80000
	s_addc_u32 s21, s89, 0
	s_add_u32 s20, s20, s26
	s_addc_u32 s21, s21, 0
	v_readfirstlane_b32 s25, v168
	v_lshrrev_b32_e32 v190, 3, v168
	v_bfe_u32 v191, v168, 4, 3
	v_and_b32_e32 v192, 7, v168
	v_xor_b32_e32 v191, v191, v192
	v_lshlrev_b32_e32 v191, 4, v191
	s_lshr_b32 s25, s25, 6
	s_lshl_b32 s25, s25, 10
	s_movk_i32 s6, 0x1000
	v_mul_lo_u32 v190, v190, s6
	v_add_u32_e32 v190, v190, v191
	v_add_u32_e32 v191, 0x20000, v190
	v_add_u32_e32 v192, 0x40000, v190
	v_add_u32_e32 v193, 0x60000, v190
	v_add_u32_e32 v194, v129, v150
	v_add_u32_e32 v198, v137, v150
	v_add_u32_e32 v195, v129, v151
	v_add_u32_e32 v199, v137, v151
	v_add_u32_e32 v196, v129, v152
	v_add_u32_e32 v200, v137, v152
	v_add_u32_e32 v197, v129, v153
	v_add_u32_e32 v201, v137, v153
	v_mov_b32_e32 v0, 0
	v_mov_b32_e32 v1, v0
	v_mov_b32_e32 v2, v0
	v_mov_b32_e32 v3, v0
	v_mov_b32_e32 v4, v0
	v_mov_b32_e32 v5, v0
	v_mov_b32_e32 v6, v0
	v_mov_b32_e32 v7, v0
	v_mov_b32_e32 v8, v0
	v_mov_b32_e32 v9, v0
	v_mov_b32_e32 v10, v0
	v_mov_b32_e32 v11, v0
	v_mov_b32_e32 v12, v0
	v_mov_b32_e32 v13, v0
	v_mov_b32_e32 v14, v0
	v_mov_b32_e32 v15, v0
	v_mov_b32_e32 v16, v0
	v_mov_b32_e32 v17, v0
	v_mov_b32_e32 v18, v0
	v_mov_b32_e32 v19, v0
	v_mov_b32_e32 v20, v0
	v_mov_b32_e32 v21, v0
	v_mov_b32_e32 v22, v0
	v_mov_b32_e32 v23, v0
	v_mov_b32_e32 v24, v0
	v_mov_b32_e32 v25, v0
	v_mov_b32_e32 v26, v0
	v_mov_b32_e32 v27, v0
	v_mov_b32_e32 v28, v0
	v_mov_b32_e32 v29, v0
	v_mov_b32_e32 v30, v0
	v_mov_b32_e32 v31, v0
	v_mov_b32_e32 v32, v0
	v_mov_b32_e32 v33, v0
	v_mov_b32_e32 v34, v0
	v_mov_b32_e32 v35, v0
	v_mov_b32_e32 v36, v0
	v_mov_b32_e32 v37, v0
	v_mov_b32_e32 v38, v0
	v_mov_b32_e32 v39, v0
	v_mov_b32_e32 v40, v0
	v_mov_b32_e32 v41, v0
	v_mov_b32_e32 v42, v0
	v_mov_b32_e32 v43, v0
	v_mov_b32_e32 v44, v0
	v_mov_b32_e32 v45, v0
	v_mov_b32_e32 v46, v0
	v_mov_b32_e32 v47, v0
	v_mov_b32_e32 v48, v0
	v_mov_b32_e32 v49, v0
	v_mov_b32_e32 v50, v0
	v_mov_b32_e32 v51, v0
	v_mov_b32_e32 v52, v0
	v_mov_b32_e32 v53, v0
	v_mov_b32_e32 v54, v0
	v_mov_b32_e32 v55, v0
	v_mov_b32_e32 v56, v0
	v_mov_b32_e32 v57, v0
	v_mov_b32_e32 v58, v0
	v_mov_b32_e32 v59, v0
	v_mov_b32_e32 v60, v0
	v_mov_b32_e32 v61, v0
	v_mov_b32_e32 v62, v0
	v_mov_b32_e32 v63, v0
	s_add_u32 m0, s25, 0x0
	s_nop 0
	global_load_lds_dwordx4 v190, s[16:17]
	s_add_u32 m0, s25, 0x1000
	s_nop 0
	global_load_lds_dwordx4 v191, s[16:17]
	s_add_u32 m0, s25, 0x2000
	s_nop 0
	global_load_lds_dwordx4 v192, s[16:17]
	s_add_u32 m0, s25, 0x3000
	s_nop 0
	global_load_lds_dwordx4 v193, s[16:17]
	s_add_u32 m0, s25, 0x8000
	s_nop 0
	global_load_lds_dwordx4 v190, s[20:21]
	s_add_u32 m0, s25, 0x9000
	s_nop 0
	global_load_lds_dwordx4 v191, s[20:21]
	s_add_u32 m0, s25, 0xa000
	s_nop 0
	global_load_lds_dwordx4 v192, s[20:21]
	s_add_u32 m0, s25, 0xb000
	s_nop 0
	global_load_lds_dwordx4 v193, s[20:21]
	s_add_u32 s16, s16, 0x80
	s_addc_u32 s17, s17, 0
	s_add_u32 s20, s20, 0x80
	s_addc_u32 s21, s21, 0
	s_add_u32 m0, s25, 0x4000
	s_nop 0
	global_load_lds_dwordx4 v190, s[16:17]
	s_add_u32 m0, s25, 0x5000
	s_nop 0
	global_load_lds_dwordx4 v191, s[16:17]
	s_add_u32 m0, s25, 0x6000
	s_nop 0
	global_load_lds_dwordx4 v192, s[16:17]
	s_add_u32 m0, s25, 0x7000
	s_nop 0
	global_load_lds_dwordx4 v193, s[16:17]
	s_add_u32 m0, s25, 0xc000
	s_nop 0
	global_load_lds_dwordx4 v190, s[20:21]
	s_add_u32 m0, s25, 0xd000
	s_nop 0
	global_load_lds_dwordx4 v191, s[20:21]
	s_add_u32 m0, s25, 0xe000
	s_nop 0
	global_load_lds_dwordx4 v192, s[20:21]
	s_add_u32 m0, s25, 0xf000
	s_nop 0
	global_load_lds_dwordx4 v193, s[20:21]
	s_add_u32 s16, s16, 0x80
	s_addc_u32 s17, s17, 0
	s_add_u32 s20, s20, 0x80
	s_addc_u32 s21, s21, 0
	s_waitcnt vmcnt(8)
	s_barrier
	ds_read_b128 v[64:67], v194 offset:0
	ds_read_b128 v[68:71], v194 offset:4096
	ds_read_b128 v[72:75], v198 offset:32768
	ds_read_b128 v[76:79], v198 offset:36864
	ds_read_b128 v[80:83], v195 offset:0
	ds_read_b128 v[84:87], v195 offset:4096
	ds_read_b128 v[88:91], v199 offset:32768
	ds_read_b128 v[92:95], v199 offset:36864
	ds_read_b128 v[96:99], v196 offset:0
	ds_read_b128 v[100:103], v196 offset:4096
	ds_read_b128 v[104:107], v200 offset:32768
	ds_read_b128 v[108:111], v200 offset:36864
	s_mov_b32 s6, 0
.Lgm_loop_G:
	ds_read_b128 v[112:115], v197 offset:0
	ds_read_b128 v[116:119], v197 offset:4096
	ds_read_b128 v[120:123], v201 offset:32768
	ds_read_b128 v[124:127], v201 offset:36864
	s_waitcnt lgkmcnt(12)
	v_mfma_f32_32x32x16_bf16 v[48:63], v[64:67], v[72:75], v[48:63]
	v_mfma_f32_32x32x16_bf16 v[32:47], v[64:67], v[76:79], v[32:47]
	v_mfma_f32_32x32x16_bf16 v[16:31], v[68:71], v[72:75], v[16:31]
	v_mfma_f32_32x32x16_bf16 v[0:15], v[68:71], v[76:79], v[0:15]
	s_waitcnt vmcnt(0) lgkmcnt(0)
	s_barrier
	s_cmp_lt_u32 s6, 30
	s_cbranch_scc0 .Lgm_nodma0_G
	s_add_u32 m0, s25, 0x0
	s_nop 0
	global_load_lds_dwordx4 v190, s[16:17]
	s_add_u32 m0, s25, 0x1000
	s_nop 0
	global_load_lds_dwordx4 v191, s[16:17]
	s_add_u32 m0, s25, 0x2000
	s_nop 0
	global_load_lds_dwordx4 v192, s[16:17]
	s_add_u32 m0, s25, 0x3000
	s_nop 0
	global_load_lds_dwordx4 v193, s[16:17]
	s_add_u32 m0, s25, 0x8000
	s_nop 0
	global_load_lds_dwordx4 v190, s[20:21]
	s_add_u32 m0, s25, 0x9000
	s_nop 0
	global_load_lds_dwordx4 v191, s[20:21]
	s_add_u32 m0, s25, 0xa000
	s_nop 0
	global_load_lds_dwordx4 v192, s[20:21]
	s_add_u32 m0, s25, 0xb000
	s_nop 0
	global_load_lds_dwordx4 v193, s[20:21]
	s_add_u32 s16, s16, 0x80
	s_addc_u32 s17, s17, 0
	s_add_u32 s20, s20, 0x80
	s_addc_u32 s21, s21, 0
.Lgm_nodma0_G:
	ds_read_b128 v[64:67], v194 offset:16384
	ds_read_b128 v[68:71], v194 offset:20480
	ds_read_b128 v[72:75], v198 offset:49152
	ds_read_b128 v[76:79], v198 offset:53248
	v_mfma_f32_32x32x16_bf16 v[48:63], v[80:83], v[88:91], v[48:63]
	v_mfma_f32_32x32x16_bf16 v[32:47], v[80:83], v[92:95], v[32:47]
	v_mfma_f32_32x32x16_bf16 v[16:31], v[84:87], v[88:91], v[16:31]
	v_mfma_f32_32x32x16_bf16 v[0:15], v[84:87], v[92:95], v[0:15]
	ds_read_b128 v[80:83], v195 offset:16384
	ds_read_b128 v[84:87], v195 offset:20480
	ds_read_b128 v[88:91], v199 offset:49152
	ds_read_b128 v[92:95], v199 offset:53248
	v_mfma_f32_32x32x16_bf16 v[48:63], v[96:99], v[104:107], v[48:63]
	v_mfma_f32_32x32x16_bf16 v[32:47], v[96:99], v[108:111], v[32:47]
	v_mfma_f32_32x32x16_bf16 v[16:31], v[100:103], v[104:107], v[16:31]
	v_mfma_f32_32x32x16_bf16 v[0:15], v[100:103], v[108:111], v[0:15]
	ds_read_b128 v[96:99], v196 offset:16384
	ds_read_b128 v[100:103], v196 offset:20480
	ds_read_b128 v[104:107], v200 offset:49152
	ds_read_b128 v[108:111], v200 offset:53248
	v_mfma_f32_32x32x16_bf16 v[48:63], v[112:115], v[120:123], v[48:63]
	v_mfma_f32_32x32x16_bf16 v[32:47], v[112:115], v[124:127], v[32:47]
	v_mfma_f32_32x32x16_bf16 v[16:31], v[116:119], v[120:123], v[16:31]
	v_mfma_f32_32x32x16_bf16 v[0:15], v[116:119], v[124:127], v[0:15]
	ds_read_b128 v[112:115], v197 offset:16384
	ds_read_b128 v[116:119], v197 offset:20480
	ds_read_b128 v[120:123], v201 offset:49152
	ds_read_b128 v[124:127], v201 offset:53248
	s_waitcnt lgkmcnt(12)
	v_mfma_f32_32x32x16_bf16 v[48:63], v[64:67], v[72:75], v[48:63]
	v_mfma_f32_32x32x16_bf16 v[32:47], v[64:67], v[76:79], v[32:47]
	v_mfma_f32_32x32x16_bf16 v[16:31], v[68:71], v[72:75], v[16:31]
	v_mfma_f32_32x32x16_bf16 v[0:15], v[68:71], v[76:79], v[0:15]
	s_waitcnt vmcnt(0) lgkmcnt(0)
	s_barrier
	s_cmp_lt_u32 s6, 30
	s_cbranch_scc0 .Lgm_nodma1_G
	s_add_u32 m0, s25, 0x4000
	s_nop 0
	global_load_lds_dwordx4 v190, s[16:17]
	s_add_u32 m0, s25, 0x5000
	s_nop 0
	global_load_lds_dwordx4 v191, s[16:17]
	s_add_u32 m0, s25, 0x6000
	s_nop 0
	global_load_lds_dwordx4 v192, s[16:17]
	s_add_u32 m0, s25, 0x7000
	s_nop 0
	global_load_lds_dwordx4 v193, s[16:17]
	s_add_u32 m0, s25, 0xc000
	s_nop 0
	global_load_lds_dwordx4 v190, s[20:21]
	s_add_u32 m0, s25, 0xd000
	s_nop 0
	global_load_lds_dwordx4 v191, s[20:21]
	s_add_u32 m0, s25, 0xe000
	s_nop 0
	global_load_lds_dwordx4 v192, s[20:21]
	s_add_u32 m0, s25, 0xf000
	s_nop 0
	global_load_lds_dwordx4 v193, s[20:21]
	s_add_u32 s16, s16, 0x80
	s_addc_u32 s17, s17, 0
	s_add_u32 s20, s20, 0x80
	s_addc_u32 s21, s21, 0
.Lgm_nodma1_G:
	ds_read_b128 v[64:67], v194 offset:0
	ds_read_b128 v[68:71], v194 offset:4096
	ds_read_b128 v[72:75], v198 offset:32768
	ds_read_b128 v[76:79], v198 offset:36864
	v_mfma_f32_32x32x16_bf16 v[48:63], v[80:83], v[88:91], v[48:63]
	v_mfma_f32_32x32x16_bf16 v[32:47], v[80:83], v[92:95], v[32:47]
	v_mfma_f32_32x32x16_bf16 v[16:31], v[84:87], v[88:91], v[16:31]
	v_mfma_f32_32x32x16_bf16 v[0:15], v[84:87], v[92:95], v[0:15]
	ds_read_b128 v[80:83], v195 offset:0
	ds_read_b128 v[84:87], v195 offset:4096
	ds_read_b128 v[88:91], v199 offset:32768
	ds_read_b128 v[92:95], v199 offset:36864
	v_mfma_f32_32x32x16_bf16 v[48:63], v[96:99], v[104:107], v[48:63]
	v_mfma_f32_32x32x16_bf16 v[32:47], v[96:99], v[108:111], v[32:47]
	v_mfma_f32_32x32x16_bf16 v[16:31], v[100:103], v[104:107], v[16:31]
	v_mfma_f32_32x32x16_bf16 v[0:15], v[100:103], v[108:111], v[0:15]
	ds_read_b128 v[96:99], v196 offset:0
	ds_read_b128 v[100:103], v196 offset:4096
	ds_read_b128 v[104:107], v200 offset:32768
	ds_read_b128 v[108:111], v200 offset:36864
	v_mfma_f32_32x32x16_bf16 v[48:63], v[112:115], v[120:123], v[48:63]
	v_mfma_f32_32x32x16_bf16 v[32:47], v[112:115], v[124:127], v[32:47]
	v_mfma_f32_32x32x16_bf16 v[16:31], v[116:119], v[120:123], v[16:31]
	v_mfma_f32_32x32x16_bf16 v[0:15], v[116:119], v[124:127], v[0:15]
	s_add_u32 s6, s6, 2
	s_cmp_lt_u32 s6, 32
	s_cbranch_scc1 .Lgm_loop_G
	s_waitcnt lgkmcnt(0)
	s_barrier
	s_nop 7

.LBB0_1102:
	s_or_b64 exec, exec, s[0:1]
	s_lshl_b32 s0, s38, 12
	s_lshl_b32 s12, s2, 12
	s_waitcnt lgkmcnt(0)
	s_add_u32 s16, s88, 0x5f80000
	s_addc_u32 s17, s89, 0
	s_add_u32 s16, s16, s0
	s_addc_u32 s17, s17, 0
	s_add_u32 s34, s88, 0x3680000
	s_addc_u32 s35, s89, 0
	s_add_u32 s34, s34, s12
	s_addc_u32 s35, s35, 0
	v_readfirstlane_b32 s36, v168
	v_lshrrev_b32_e32 v188, 3, v168
	v_bfe_u32 v189, v168, 4, 3
	v_and_b32_e32 v190, 7, v168
	v_xor_b32_e32 v189, v189, v190
	v_lshlrev_b32_e32 v189, 4, v189
	s_lshr_b32 s36, s36, 6
	s_lshl_b32 s36, s36, 10
	s_movk_i32 s12, 0x1000
	v_mul_lo_u32 v188, v188, s12
	v_add_u32_e32 v188, v188, v189
	v_add_u32_e32 v189, 0x20000, v188
	v_add_u32_e32 v190, 0x40000, v188
	v_add_u32_e32 v191, 0x60000, v188
	v_mov_b32_e32 v0, 0
	v_mov_b32_e32 v1, v0
	v_mov_b32_e32 v2, v0
	v_mov_b32_e32 v3, v0
	v_mov_b32_e32 v4, v0
	v_mov_b32_e32 v5, v0
	v_mov_b32_e32 v6, v0
	v_mov_b32_e32 v7, v0
	v_mov_b32_e32 v8, v0
	v_mov_b32_e32 v9, v0
	v_mov_b32_e32 v10, v0
	v_mov_b32_e32 v11, v0
	v_mov_b32_e32 v12, v0
	v_mov_b32_e32 v13, v0
	v_mov_b32_e32 v14, v0
	v_mov_b32_e32 v15, v0
	v_mov_b32_e32 v16, v0
	v_mov_b32_e32 v17, v0
	v_mov_b32_e32 v18, v0
	v_mov_b32_e32 v19, v0
	v_mov_b32_e32 v20, v0
	v_mov_b32_e32 v21, v0
	v_mov_b32_e32 v22, v0
	v_mov_b32_e32 v23, v0
	v_mov_b32_e32 v24, v0
	v_mov_b32_e32 v25, v0
	v_mov_b32_e32 v26, v0
	v_mov_b32_e32 v27, v0
	v_mov_b32_e32 v28, v0
	v_mov_b32_e32 v29, v0
	v_mov_b32_e32 v30, v0
	v_mov_b32_e32 v31, v0
	v_mov_b32_e32 v32, v0
	v_mov_b32_e32 v33, v0
	v_mov_b32_e32 v34, v0
	v_mov_b32_e32 v35, v0
	v_mov_b32_e32 v36, v0
	v_mov_b32_e32 v37, v0
	v_mov_b32_e32 v38, v0
	v_mov_b32_e32 v39, v0
	v_mov_b32_e32 v40, v0
	v_mov_b32_e32 v41, v0
	v_mov_b32_e32 v42, v0
	v_mov_b32_e32 v43, v0
	v_mov_b32_e32 v44, v0
	v_mov_b32_e32 v45, v0
	v_mov_b32_e32 v46, v0
	v_mov_b32_e32 v47, v0
	v_mov_b32_e32 v48, v0
	v_mov_b32_e32 v49, v0
	v_mov_b32_e32 v50, v0
	v_mov_b32_e32 v51, v0
	v_mov_b32_e32 v52, v0
	v_mov_b32_e32 v53, v0
	v_mov_b32_e32 v54, v0
	v_mov_b32_e32 v55, v0
	v_mov_b32_e32 v56, v0
	v_mov_b32_e32 v57, v0
	v_mov_b32_e32 v58, v0
	v_mov_b32_e32 v59, v0
	v_mov_b32_e32 v60, v0
	v_mov_b32_e32 v61, v0
	v_mov_b32_e32 v62, v0
	v_mov_b32_e32 v63, v0
	s_add_u32 m0, s36, 0x0
	s_nop 0
	global_load_lds_dwordx4 v188, s[16:17]
	s_add_u32 m0, s36, 0x1000
	s_nop 0
	global_load_lds_dwordx4 v189, s[16:17]
	s_add_u32 m0, s36, 0x2000
	s_nop 0
	global_load_lds_dwordx4 v190, s[16:17]
	s_add_u32 m0, s36, 0x3000
	s_nop 0
	global_load_lds_dwordx4 v191, s[16:17]
	s_add_u32 m0, s36, 0x8000
	s_nop 0
	global_load_lds_dwordx4 v188, s[34:35]
	s_add_u32 m0, s36, 0x9000
	s_nop 0
	global_load_lds_dwordx4 v189, s[34:35]
	s_add_u32 m0, s36, 0xa000
	s_nop 0
	global_load_lds_dwordx4 v190, s[34:35]
	s_add_u32 m0, s36, 0xb000
	s_nop 0
	global_load_lds_dwordx4 v191, s[34:35]
	s_add_u32 s16, s16, 0x80
	s_addc_u32 s17, s17, 0
	s_add_u32 s34, s34, 0x80
	s_addc_u32 s35, s35, 0
	s_add_u32 m0, s36, 0x4000
	s_nop 0
	global_load_lds_dwordx4 v188, s[16:17]
	s_add_u32 m0, s36, 0x5000
	s_nop 0
	global_load_lds_dwordx4 v189, s[16:17]
	s_add_u32 m0, s36, 0x6000
	s_nop 0
	global_load_lds_dwordx4 v190, s[16:17]
	s_add_u32 m0, s36, 0x7000
	s_nop 0
	global_load_lds_dwordx4 v191, s[16:17]
	s_add_u32 m0, s36, 0xc000
	s_nop 0
	global_load_lds_dwordx4 v188, s[34:35]
	s_add_u32 m0, s36, 0xd000
	s_nop 0
	global_load_lds_dwordx4 v189, s[34:35]
	s_add_u32 m0, s36, 0xe000
	s_nop 0
	global_load_lds_dwordx4 v190, s[34:35]
	s_add_u32 m0, s36, 0xf000
	s_nop 0
	global_load_lds_dwordx4 v191, s[34:35]
	s_add_u32 s16, s16, 0x80
	s_addc_u32 s17, s17, 0
	s_add_u32 s34, s34, 0x80
	s_addc_u32 s35, s35, 0
	s_waitcnt vmcnt(8)
	s_barrier
	ds_read_b128 v[64:67], v177 offset:0
	ds_read_b128 v[68:71], v177 offset:4096
	ds_read_b128 v[72:75], v178 offset:32768
	ds_read_b128 v[76:79], v178 offset:36864
	ds_read_b128 v[80:83], v179 offset:0
	ds_read_b128 v[84:87], v179 offset:4096
	ds_read_b128 v[88:91], v182 offset:32768
	ds_read_b128 v[92:95], v182 offset:36864
	ds_read_b128 v[96:99], v183 offset:0
	ds_read_b128 v[100:103], v183 offset:4096
	ds_read_b128 v[104:107], v184 offset:32768
	ds_read_b128 v[108:111], v184 offset:36864
	s_mov_b32 s12, 0
.Lgm_loop_H:
	ds_read_b128 v[112:115], v185 offset:0
	ds_read_b128 v[116:119], v185 offset:4096
	ds_read_b128 v[120:123], v186 offset:32768
	ds_read_b128 v[124:127], v186 offset:36864
	s_waitcnt lgkmcnt(12)
	v_mfma_f32_32x32x16_bf16 v[48:63], v[64:67], v[72:75], v[48:63]
	v_mfma_f32_32x32x16_bf16 v[32:47], v[64:67], v[76:79], v[32:47]
	v_mfma_f32_32x32x16_bf16 v[16:31], v[68:71], v[72:75], v[16:31]
	v_mfma_f32_32x32x16_bf16 v[0:15], v[68:71], v[76:79], v[0:15]
	s_waitcnt vmcnt(0) lgkmcnt(0)
	s_barrier
	s_cmp_lt_u32 s12, 30
	s_cbranch_scc0 .Lgm_nodma0_H
	s_add_u32 m0, s36, 0x0
	s_nop 0
	global_load_lds_dwordx4 v188, s[16:17]
	s_add_u32 m0, s36, 0x1000
	s_nop 0
	global_load_lds_dwordx4 v189, s[16:17]
	s_add_u32 m0, s36, 0x2000
	s_nop 0
	global_load_lds_dwordx4 v190, s[16:17]
	s_add_u32 m0, s36, 0x3000
	s_nop 0
	global_load_lds_dwordx4 v191, s[16:17]
	s_add_u32 m0, s36, 0x8000
	s_nop 0
	global_load_lds_dwordx4 v188, s[34:35]
	s_add_u32 m0, s36, 0x9000
	s_nop 0
	global_load_lds_dwordx4 v189, s[34:35]
	s_add_u32 m0, s36, 0xa000
	s_nop 0
	global_load_lds_dwordx4 v190, s[34:35]
	s_add_u32 m0, s36, 0xb000
	s_nop 0
	global_load_lds_dwordx4 v191, s[34:35]
	s_add_u32 s16, s16, 0x80
	s_addc_u32 s17, s17, 0
	s_add_u32 s34, s34, 0x80
	s_addc_u32 s35, s35, 0
.Lgm_nodma0_H:
	ds_read_b128 v[64:67], v177 offset:16384
	ds_read_b128 v[68:71], v177 offset:20480
	ds_read_b128 v[72:75], v178 offset:49152
	ds_read_b128 v[76:79], v178 offset:53248
	v_mfma_f32_32x32x16_bf16 v[48:63], v[80:83], v[88:91], v[48:63]
	v_mfma_f32_32x32x16_bf16 v[32:47], v[80:83], v[92:95], v[32:47]
	v_mfma_f32_32x32x16_bf16 v[16:31], v[84:87], v[88:91], v[16:31]
	v_mfma_f32_32x32x16_bf16 v[0:15], v[84:87], v[92:95], v[0:15]
	ds_read_b128 v[80:83], v179 offset:16384
	ds_read_b128 v[84:87], v179 offset:20480
	ds_read_b128 v[88:91], v182 offset:49152
	ds_read_b128 v[92:95], v182 offset:53248
	v_mfma_f32_32x32x16_bf16 v[48:63], v[96:99], v[104:107], v[48:63]
	v_mfma_f32_32x32x16_bf16 v[32:47], v[96:99], v[108:111], v[32:47]
	v_mfma_f32_32x32x16_bf16 v[16:31], v[100:103], v[104:107], v[16:31]
	v_mfma_f32_32x32x16_bf16 v[0:15], v[100:103], v[108:111], v[0:15]
	ds_read_b128 v[96:99], v183 offset:16384
	ds_read_b128 v[100:103], v183 offset:20480
	ds_read_b128 v[104:107], v184 offset:49152
	ds_read_b128 v[108:111], v184 offset:53248
	v_mfma_f32_32x32x16_bf16 v[48:63], v[112:115], v[120:123], v[48:63]
	v_mfma_f32_32x32x16_bf16 v[32:47], v[112:115], v[124:127], v[32:47]
	v_mfma_f32_32x32x16_bf16 v[16:31], v[116:119], v[120:123], v[16:31]
	v_mfma_f32_32x32x16_bf16 v[0:15], v[116:119], v[124:127], v[0:15]
	ds_read_b128 v[112:115], v185 offset:16384
	ds_read_b128 v[116:119], v185 offset:20480
	ds_read_b128 v[120:123], v186 offset:49152
	ds_read_b128 v[124:127], v186 offset:53248
	s_waitcnt lgkmcnt(12)
	v_mfma_f32_32x32x16_bf16 v[48:63], v[64:67], v[72:75], v[48:63]
	v_mfma_f32_32x32x16_bf16 v[32:47], v[64:67], v[76:79], v[32:47]
	v_mfma_f32_32x32x16_bf16 v[16:31], v[68:71], v[72:75], v[16:31]
	v_mfma_f32_32x32x16_bf16 v[0:15], v[68:71], v[76:79], v[0:15]
	s_waitcnt vmcnt(0) lgkmcnt(0)
	s_barrier
	s_cmp_lt_u32 s12, 30
	s_cbranch_scc0 .Lgm_nodma1_H
	s_add_u32 m0, s36, 0x4000
	s_nop 0
	global_load_lds_dwordx4 v188, s[16:17]
	s_add_u32 m0, s36, 0x5000
	s_nop 0
	global_load_lds_dwordx4 v189, s[16:17]
	s_add_u32 m0, s36, 0x6000
	s_nop 0
	global_load_lds_dwordx4 v190, s[16:17]
	s_add_u32 m0, s36, 0x7000
	s_nop 0
	global_load_lds_dwordx4 v191, s[16:17]
	s_add_u32 m0, s36, 0xc000
	s_nop 0
	global_load_lds_dwordx4 v188, s[34:35]
	s_add_u32 m0, s36, 0xd000
	s_nop 0
	global_load_lds_dwordx4 v189, s[34:35]
	s_add_u32 m0, s36, 0xe000
	s_nop 0
	global_load_lds_dwordx4 v190, s[34:35]
	s_add_u32 m0, s36, 0xf000
	s_nop 0
	global_load_lds_dwordx4 v191, s[34:35]
	s_add_u32 s16, s16, 0x80
	s_addc_u32 s17, s17, 0
	s_add_u32 s34, s34, 0x80
	s_addc_u32 s35, s35, 0
.Lgm_nodma1_H:
	ds_read_b128 v[64:67], v177 offset:0
	ds_read_b128 v[68:71], v177 offset:4096
	ds_read_b128 v[72:75], v178 offset:32768
	ds_read_b128 v[76:79], v178 offset:36864
	v_mfma_f32_32x32x16_bf16 v[48:63], v[80:83], v[88:91], v[48:63]
	v_mfma_f32_32x32x16_bf16 v[32:47], v[80:83], v[92:95], v[32:47]
	v_mfma_f32_32x32x16_bf16 v[16:31], v[84:87], v[88:91], v[16:31]
	v_mfma_f32_32x32x16_bf16 v[0:15], v[84:87], v[92:95], v[0:15]
	ds_read_b128 v[80:83], v179 offset:0
	ds_read_b128 v[84:87], v179 offset:4096
	ds_read_b128 v[88:91], v182 offset:32768
	ds_read_b128 v[92:95], v182 offset:36864
	v_mfma_f32_32x32x16_bf16 v[48:63], v[96:99], v[104:107], v[48:63]
	v_mfma_f32_32x32x16_bf16 v[32:47], v[96:99], v[108:111], v[32:47]
	v_mfma_f32_32x32x16_bf16 v[16:31], v[100:103], v[104:107], v[16:31]
	v_mfma_f32_32x32x16_bf16 v[0:15], v[100:103], v[108:111], v[0:15]
	ds_read_b128 v[96:99], v183 offset:0
	ds_read_b128 v[100:103], v183 offset:4096
	ds_read_b128 v[104:107], v184 offset:32768
	ds_read_b128 v[108:111], v184 offset:36864
	v_mfma_f32_32x32x16_bf16 v[48:63], v[112:115], v[120:123], v[48:63]
	v_mfma_f32_32x32x16_bf16 v[32:47], v[112:115], v[124:127], v[32:47]
	v_mfma_f32_32x32x16_bf16 v[16:31], v[116:119], v[120:123], v[16:31]
	v_mfma_f32_32x32x16_bf16 v[0:15], v[116:119], v[124:127], v[0:15]
	s_add_u32 s12, s12, 2
	s_cmp_lt_u32 s12, 32
	s_cbranch_scc1 .Lgm_loop_H
	s_waitcnt lgkmcnt(0)
	s_barrier
	s_nop 7
